# half-tile stagger (10us) of blocks>=256 at start of UP GEMM phases P4/P9 to overlap epilogues with K loops on L2
# speedup vs baseline: 1.0095x; 1.0086x over previous
.LBB0_335:
	s_or_b64 exec, exec, s[6:7]
	v_and_b32_e32 v2, 0x3ff, v0
	s_barrier
	s_cmpk_lt_u32 s2, 0x100
	s_cbranch_scc1 .Lstg2_done_4
	s_memrealtime s[12:13]
	s_waitcnt lgkmcnt(0)
	s_add_u32 s3, s12, 1000
.Lstg2_spin_4:
	s_sleep 2
	s_memrealtime s[12:13]
	s_waitcnt lgkmcnt(0)
	s_sub_u32 s13, s3, s12
	s_cmp_gt_i32 s13, 0
	s_cbranch_scc1 .Lstg2_spin_4
.Lstg2_done_4:
.LBB0_336:
	s_cmpk_gt_u32 s2, 0x1fff
	v_readfirstlane_b32 s8, v2
	s_cbranch_scc1 .LBB0_339
	v_lshrrev_b32_e32 v3, 3, v2
	v_lshlrev_b32_e32 v5, 3, v2
	v_lshlrev_b32_e32 v4, 4, v2
	v_mov_b32_e32 v67, 0
	v_lshlrev_b32_e32 v66, 11, v3
	v_readlane_b32 s14, v252, 2
	s_add_u32 s6, s82, 0xae60000
	v_and_b32_e32 v4, 0x70, v4
	v_and_b32_e32 v6, 0x78, v5
	v_lshl_add_u64 v[8:9], s[92:93], 0, v[66:67]
	v_mov_b32_e32 v5, v67
	v_readlane_b32 s15, v252, 3
	s_load_dword s10, s[0:1], 0x1b8
	s_addc_u32 s7, s83, 0
	v_lshl_add_u64 v[68:69], v[8:9], 0, v[4:5]
	v_lshl_add_u64 v[8:9], s[14:15], 0, v[66:67]
	s_bfe_u32 s14, s8, 0x10006
	s_lshr_b32 s8, s8, 1
	v_mul_u32_u24_e32 v1, 0x48, v3
	v_lshrrev_b32_e32 v93, 4, v2
	v_bfe_u32 v3, v2, 5, 1
	v_and_b32_e32 v2, 31, v2
	s_and_b32 s15, s8, 0x7fffffc0
	v_lshl_add_u32 v1, v1, 1, v4
	v_lshl_add_u64 v[70:71], v[8:9], 0, v[4:5]
	v_lshlrev_b32_e32 v4, 4, v3
	v_or_b32_e32 v5, s15, v2
	s_movk_i32 s16, 0x90
	s_movk_i32 s11, 0x204
	v_mad_u64_u32 v[72:73], s[8:9], v5, s16, v[4:5]
	v_lshl_or_b32 v3, v3, 2, s15
	v_lshlrev_b32_e32 v7, 2, v6
	v_mul_u32_u24_e32 v10, 0x204, v93
	v_lshl_or_b32 v5, s14, 6, v2
	v_mul_lo_u32 v3, v3, s11
	s_lshl_b32 s8, s14, 8
	v_lshlrev_b32_e32 v2, 2, v2
	s_waitcnt lgkmcnt(0)
	s_lshr_b32 s12, s10, 3
	s_lshr_b32 s13, s2, 3
	v_add3_u32 v101, s8, v3, v2
	v_add_u32_e32 v103, v7, v10
	s_and_b32 s3, s2, 7
	v_add_u32_e32 v92, 0x9000, v1
	v_add_u32_e32 v94, 16, v93
	v_add_u32_e32 v95, 32, v93
	v_add_u32_e32 v96, 48, v93
	v_or_b32_e32 v97, 64, v93
	v_add_u32_e32 v98, 0x50, v93
	v_add_u32_e32 v99, 0x60, v93
	v_add_u32_e32 v100, 0x70, v93
	v_mad_u32_u24 v73, v5, s16, v4
	s_lshl_b32 s14, s13, 4
	s_lshl_b32 s15, s12, 4
	s_and_b32 s16, s2, -8
	s_and_b32 s17, s10, -8
	s_mov_b32 s9, 0
	s_mov_b32 s18, 0x10000
	s_mov_b32 s19, 0x20000
	s_mov_b32 s20, 0x30000
	v_mov_b32_e32 v102, 0x358637bd
	s_mov_b32 s21, 0x800000
	v_lshlrev_b32_e32 v74, 1, v6
	v_mov_b32_e32 v75, v67
	s_movk_i32 s22, 0x7fff
	v_add_u32_e32 v104, 0x2040, v103
	v_add_u32_e32 v105, 0x2048, v103
	v_add_u32_e32 v106, 0x2050, v103
	v_add_u32_e32 v107, 0x2058, v103
	v_add_u32_e32 v108, 0x4080, v103
	v_add_u32_e32 v109, 0x4088, v103
	v_add_u32_e32 v110, 0x4090, v103
	v_add_u32_e32 v111, 0x4098, v103
	v_add_u32_e32 v112, 0x60c0, v103
	v_add_u32_e32 v113, 0x60c8, v103
	v_add_u32_e32 v114, 0x60d0, v103
	v_add_u32_e32 v115, 0x60d8, v103
	v_add_u32_e32 v116, 0x8100, v103
	v_add_u32_e32 v117, 0x8108, v103
	v_add_u32_e32 v118, 0x8110, v103
	v_add_u32_e32 v119, 0x8118, v103
	v_add_u32_e32 v120, 0xa140, v103
	v_add_u32_e32 v121, 0xa148, v103
	v_add_u32_e32 v122, 0xa150, v103
	v_add_u32_e32 v123, 0xa158, v103
	v_add_u32_e32 v124, 0xc180, v103
	v_add_u32_e32 v125, 0xc188, v103
	v_add_u32_e32 v126, 0xc190, v103
	v_add_u32_e32 v127, 0xc198, v103
	v_add_u32_e32 v128, 0xe1c0, v103
	v_add_u32_e32 v129, 0xe1c8, v103
	v_add_u32_e32 v130, 0xe1d0, v103
	v_add_u32_e32 v131, 0xe1d8, v103
	v_add_u32_e32 v132, 0x4000, v101
	v_add_u32_e32 v133, 0x400, v101
	v_add_u32_e32 v134, 0x4400, v101
	v_add_u32_e32 v135, 0x1000, v101
	v_add_u32_e32 v136, 0x5000, v101
	v_add_u32_e32 v137, 0x1400, v101
	v_add_u32_e32 v138, 0x5400, v101
	v_add_u32_e32 v139, 0x2000, v101
	v_add_u32_e32 v140, 0x6000, v101
	v_add_u32_e32 v141, 0x2400, v101
	v_add_u32_e32 v142, 0x6400, v101
	v_add_u32_e32 v143, 0x3000, v101
	v_add_u32_e32 v144, 0x7000, v101
	v_add_u32_e32 v145, 0x3400, v101
	v_add_u32_e32 v146, 0x7400, v101
	v_mov_b32_e32 v147, 1

.Lstg2_done_9:
.LBB0_588:
	s_cmpk_gt_u32 s2, 0x1fff
	v_readfirstlane_b32 s8, v2
	s_cbranch_scc1 .LBB0_591
	s_add_u32 s6, s82, 0xaea0000
	s_addc_u32 s7, s83, 0
	s_bfe_u32 s11, s8, 0x10006
	s_lshr_b32 s8, s8, 1
	v_bfe_u32 v3, v2, 5, 1
	v_and_b32_e32 v5, 31, v2
	s_and_b32 s14, s8, 0x7fffffc0
	v_lshrrev_b32_e32 v7, 3, v2
	v_or_b32_e32 v9, s14, v5
	v_lshlrev_b32_e32 v6, 4, v3
	s_movk_i32 s15, 0x90
	s_load_dword s10, s[0:1], 0x1b8
	v_mad_u64_u32 v[66:67], s[8:9], v9, s15, v[6:7]
	v_lshl_or_b32 v3, v3, 2, s14
	s_movk_i32 s8, 0x204
	v_lshlrev_b32_e32 v8, 3, v2
	v_lshl_or_b32 v9, s11, 6, v5
	v_mul_lo_u32 v3, v3, s8
	s_lshl_b32 s8, s11, 8
	v_lshlrev_b32_e32 v5, 2, v5
	v_lshlrev_b32_e32 v4, 4, v2
	v_add3_u32 v93, s8, v3, v5
	v_lshrrev_b32_e32 v94, 4, v2
	v_and_b32_e32 v2, 0x78, v8
	v_mov_b32_e32 v69, 0
	v_lshlrev_b32_e32 v68, 11, v7
	v_readlane_b32 s8, v252, 6
	v_mul_u32_u24_e32 v1, 0x48, v7
	v_and_b32_e32 v4, 0x70, v4
	v_mad_u32_u24 v67, v9, s15, v6
	v_lshlrev_b32_e32 v3, 2, v2
	v_mul_u32_u24_e32 v8, 0x204, v94
	v_lshl_add_u64 v[6:7], s[92:93], 0, v[68:69]
	v_mov_b32_e32 v5, v69
	v_readlane_b32 s9, v252, 7
	s_lshr_b32 s12, s2, 3
	s_waitcnt lgkmcnt(0)
	s_lshr_b32 s13, s10, 3
	v_lshl_add_u32 v1, v1, 1, v4
	v_lshl_add_u64 v[70:71], v[6:7], 0, v[4:5]
	v_lshl_add_u64 v[6:7], s[8:9], 0, v[68:69]
	v_add_u32_e32 v103, v3, v8
	s_and_b32 s3, s2, 7
	v_add_u32_e32 v92, 0x9000, v1
	v_add_u32_e32 v95, 16, v94
	v_add_u32_e32 v96, 32, v94
	v_add_u32_e32 v97, 48, v94
	v_or_b32_e32 v98, 64, v94
	v_add_u32_e32 v99, 0x50, v94
	v_add_u32_e32 v100, 0x60, v94
	v_add_u32_e32 v101, 0x70, v94
	v_lshl_add_u64 v[72:73], v[6:7], 0, v[4:5]
	s_lshl_b32 s14, s12, 4
	s_lshl_b32 s15, s13, 4
	s_and_b32 s16, s2, -8
	s_and_b32 s17, s10, -8
	s_mov_b32 s9, 0
	s_mov_b32 s18, 0x10000
	s_mov_b32 s19, 0x20000
	s_mov_b32 s20, 0x30000
	v_mov_b32_e32 v102, 0x358637bd
	s_mov_b32 s21, 0x800000
	v_lshlrev_b32_e32 v74, 1, v2
	v_mov_b32_e32 v75, v69
	s_movk_i32 s22, 0x7fff
	v_add_u32_e32 v104, 0x2040, v103
	v_add_u32_e32 v105, 0x2048, v103
	v_add_u32_e32 v106, 0x2050, v103
	v_add_u32_e32 v107, 0x2058, v103
	v_add_u32_e32 v108, 0x4080, v103
	v_add_u32_e32 v109, 0x4088, v103
	v_add_u32_e32 v110, 0x4090, v103
	v_add_u32_e32 v111, 0x4098, v103
	v_add_u32_e32 v112, 0x60c0, v103
	v_add_u32_e32 v113, 0x60c8, v103
	v_add_u32_e32 v114, 0x60d0, v103
	v_add_u32_e32 v115, 0x60d8, v103
	v_add_u32_e32 v116, 0x8100, v103
	v_add_u32_e32 v117, 0x8108, v103
	v_add_u32_e32 v118, 0x8110, v103
	v_add_u32_e32 v119, 0x8118, v103
	v_add_u32_e32 v120, 0xa140, v103
	v_add_u32_e32 v121, 0xa148, v103
	v_add_u32_e32 v122, 0xa150, v103
	v_add_u32_e32 v123, 0xa158, v103
	v_add_u32_e32 v124, 0xc180, v103
	v_add_u32_e32 v125, 0xc188, v103
	v_add_u32_e32 v126, 0xc190, v103
	v_add_u32_e32 v127, 0xc198, v103
	v_add_u32_e32 v128, 0xe1c0, v103
	v_add_u32_e32 v129, 0xe1c8, v103
	v_add_u32_e32 v130, 0xe1d0, v103
	v_add_u32_e32 v131, 0xe1d8, v103
	v_add_u32_e32 v132, 0x4000, v93
	v_add_u32_e32 v133, 0x400, v93
	v_add_u32_e32 v134, 0x4400, v93
	v_add_u32_e32 v135, 0x1000, v93
	v_add_u32_e32 v136, 0x5000, v93
	v_add_u32_e32 v137, 0x1400, v93
	v_add_u32_e32 v138, 0x5400, v93
	v_add_u32_e32 v139, 0x2000, v93
	v_add_u32_e32 v140, 0x6000, v93
	v_add_u32_e32 v141, 0x2400, v93
	v_add_u32_e32 v142, 0x6400, v93
	v_add_u32_e32 v143, 0x3000, v93
	v_add_u32_e32 v144, 0x7000, v93
	v_add_u32_e32 v145, 0x3400, v93
	v_add_u32_e32 v146, 0x7400, v93
	v_mov_b32_e32 v147, 1
